# combo8: combo7 + hand-written grid barrier for the 7 in-loop seams (hierarchical arrive on XSUB/TOP, every workgroup polls TOP directly: no TOPGEN/XGEN release hops)
# speedup vs baseline: 1.0114x; 1.0015x over previous
; __device__ __forceinline__ unsigned xb_ld(unsigned* p)              { return __hip_atomic_load(p, __ATOMIC_RELAXED, __HIP_MEMORY_SCOPE_AGENT); }
; __device__ __forceinline__ unsigned xb_add(unsigned* p, unsigned v) { return __hip_atomic_fetch_add(p, v, __ATOMIC_RELAXED, __HIP_MEMORY_SCOPE_AGENT); }
; #define XB_SPIN(cond, bar) do { unsigned _sp = 0; while (cond) { __builtin_amdgcn_s_sleep(1); \
;     if ((++_sp & 255u) == 0u) { if (xb_ld(&(bar)[XB_TMO])) break; if (_sp > XB_SPIN_CAP) { atomicAdd(&(bar)[XB_TMO], 1u); break; } } } } while (0)
; __device__ __forceinline__ void xcd_barrier(const XcdBarrier& b) {
;     asm volatile("s_waitcnt vmcnt(0)" ::: "memory");
;     __syncthreads();
;     if (threadIdx.x == 0) {
;         unsigned* bar = b.bar; unsigned bx = b.x; asm volatile("" : "+s"(bx));
;         __builtin_amdgcn_s_waitcnt(0);
;         unsigned nloc = b.st[0], nx = b.st[1];
;         if (nloc == 0u) { xcd_barrier_complete(bar, bx, nloc, nx); b.st[0] = nloc; b.st[1] = nx; }
;         const unsigned old = xb_add(&bar[XB_XSUB(bx)], 1u);
;         const unsigned gen = old / nloc;
;         if (old + 1u == (gen + 1u) * nloc) {
;             __builtin_amdgcn_fence(__ATOMIC_RELEASE, "agent");
;             asm volatile("s_waitcnt vmcnt(0)" ::: "memory");
;             const unsigned og = xb_add(&bar[XB_TOP], 1u);
;             const unsigned tg = og / nx;
;             if (og + 1u == (tg + 1u) * nx) xb_add(&bar[XB_TOPGEN], 1u);
;             else XB_SPIN(xb_ld(&bar[XB_TOPGEN]) == tg, bar);
;             __builtin_amdgcn_fence(__ATOMIC_ACQUIRE, "agent");
;             xb_add(&bar[XB_XGEN(bx)], 1u);
;             asm volatile("s_waitcnt vmcnt(0)" ::: "memory");
;         } else {
;             XB_SPIN(xb_ld(&bar[XB_XGEN(bx)]) == gen, bar);
;             __builtin_amdgcn_fence(__ATOMIC_ACQUIRE, "agent");
;             asm volatile("s_waitcnt vmcnt(0)" ::: "memory");
;         }
.LBB0_243:
	s_waitcnt vmcnt(0)
	s_barrier
	s_mov_b64 s[0:1], exec
	v_readlane_b32 s2, v252, 3
	v_readlane_b32 s3, v252, 4
	s_and_b64 s[2:3], s[0:1], s[2:3]
	s_mov_b64 exec, s[2:3]
	s_cbranch_execz .LBB0_295
	s_waitcnt vmcnt(0) lgkmcnt(0)
	v_mov_b32_e32 v0, 0x26800
	ds_read_b32 v2, v0
	ds_read_b32 v3, v0 offset:4
	v_readlane_b32 s10, v252, 0
	v_readlane_b32 s11, v252, 1
	v_readlane_b32 s12, v252, 2
	s_lshl_b32 s12, s12, 8
	s_add_u32 s14, s10, s12
	s_addc_u32 s15, s11, 0
	s_add_u32 s14, s14, 0x1400
	s_addc_u32 s15, s15, 0
	s_add_u32 s16, s10, 0x3400
	s_addc_u32 s17, s11, 0
	v_mov_b32_e32 v4, 1
	global_atomic_add v5, v161, v4, s[14:15] sc0
	s_waitcnt lgkmcnt(0)
	v_readfirstlane_b32 s18, v2
	v_readfirstlane_b32 s19, v3
	v_cvt_f32_u32_e32 v7, v2
	v_rcp_f32_e32 v7, v7
	s_waitcnt vmcnt(0)
	v_readfirstlane_b32 s13, v5
	v_cvt_f32_u32_e32 v6, v5
	v_mul_f32_e32 v6, v6, v7
	v_cvt_u32_f32_e32 v6, v6
	s_nop 0
	v_readfirstlane_b32 s2, v6
	s_mul_i32 s3, s2, s18
	s_cmp_gt_u32 s3, s13
	s_cbranch_scc0 .Lxb0_a
	s_sub_i32 s2, s2, 1
	s_sub_i32 s3, s3, s18
.Lxb0_a:
	s_add_i32 s3, s3, s18
	s_cmp_le_u32 s3, s13
	s_cbranch_scc0 .Lxb0_b
	s_add_i32 s2, s2, 1
	s_add_i32 s3, s3, s18
.Lxb0_b:
	s_add_i32 s13, s13, 1
	s_cmp_eq_u32 s13, s3
	s_cbranch_scc0 .Lxb0_poll
	buffer_wbl2 sc1
	s_waitcnt vmcnt(0)
	global_atomic_add v161, v4, s[16:17]
.Lxb0_poll:
	s_add_i32 s2, s2, 1
	s_mul_i32 s2, s2, s19
	s_mov_b32 s3, 0
.Lxb0_spin:
	global_load_dword v5, v161, s[16:17] sc1
	s_waitcnt vmcnt(0)
	v_readfirstlane_b32 s12, v5
	s_cmp_ge_u32 s12, s2
	s_cbranch_scc1 .Lxb0_go
	s_sleep 1
	s_add_i32 s3, s3, 1
	s_cmp_lt_u32 s3, 0x1000
	s_cbranch_scc1 .Lxb0_spin
.Lxb0_go:
	buffer_inv sc1
	s_waitcnt vmcnt(0)

; __device__ __forceinline__ unsigned xb_ld(unsigned* p)              { return __hip_atomic_load(p, __ATOMIC_RELAXED, __HIP_MEMORY_SCOPE_AGENT); }
; __device__ __forceinline__ unsigned xb_add(unsigned* p, unsigned v) { return __hip_atomic_fetch_add(p, v, __ATOMIC_RELAXED, __HIP_MEMORY_SCOPE_AGENT); }
; #define XB_SPIN(cond, bar) do { unsigned _sp = 0; while (cond) { __builtin_amdgcn_s_sleep(1); \
;     if ((++_sp & 255u) == 0u) { if (xb_ld(&(bar)[XB_TMO])) break; if (_sp > XB_SPIN_CAP) { atomicAdd(&(bar)[XB_TMO], 1u); break; } } } } while (0)
; __device__ __forceinline__ void xcd_barrier(const XcdBarrier& b) {
;     asm volatile("s_waitcnt vmcnt(0)" ::: "memory");
;     __syncthreads();
;     if (threadIdx.x == 0) {
;         unsigned* bar = b.bar; unsigned bx = b.x; asm volatile("" : "+s"(bx));
;         __builtin_amdgcn_s_waitcnt(0);
;         unsigned nloc = b.st[0], nx = b.st[1];
;         if (nloc == 0u) { xcd_barrier_complete(bar, bx, nloc, nx); b.st[0] = nloc; b.st[1] = nx; }
;         const unsigned old = xb_add(&bar[XB_XSUB(bx)], 1u);
;         const unsigned gen = old / nloc;
;         if (old + 1u == (gen + 1u) * nloc) {
;             __builtin_amdgcn_fence(__ATOMIC_RELEASE, "agent");
;             asm volatile("s_waitcnt vmcnt(0)" ::: "memory");
;             const unsigned og = xb_add(&bar[XB_TOP], 1u);
;             const unsigned tg = og / nx;
;             if (og + 1u == (tg + 1u) * nx) xb_add(&bar[XB_TOPGEN], 1u);
;             else XB_SPIN(xb_ld(&bar[XB_TOPGEN]) == tg, bar);
;             __builtin_amdgcn_fence(__ATOMIC_ACQUIRE, "agent");
;             xb_add(&bar[XB_XGEN(bx)], 1u);
;             asm volatile("s_waitcnt vmcnt(0)" ::: "memory");
;         } else {
;             XB_SPIN(xb_ld(&bar[XB_XGEN(bx)]) == gen, bar);
;             __builtin_amdgcn_fence(__ATOMIC_ACQUIRE, "agent");
;             asm volatile("s_waitcnt vmcnt(0)" ::: "memory");
;         }
.LBB0_303:
	s_or_b64 exec, exec, s[2:3]
	s_waitcnt vmcnt(0)
	s_waitcnt vmcnt(63) expcnt(7) lgkmcnt(15)
	s_barrier
	s_mov_b64 s[0:1], exec
	v_readlane_b32 s2, v252, 3
	v_readlane_b32 s3, v252, 4
	s_and_b64 s[2:3], s[0:1], s[2:3]
	s_mov_b64 exec, s[2:3]
	s_cbranch_execz .LBB0_355
	s_waitcnt vmcnt(0) lgkmcnt(0)
	v_mov_b32_e32 v0, 0x26800
	ds_read_b32 v2, v0
	ds_read_b32 v3, v0 offset:4
	v_readlane_b32 s10, v252, 0
	v_readlane_b32 s11, v252, 1
	v_readlane_b32 s12, v252, 2
	s_lshl_b32 s12, s12, 8
	s_add_u32 s14, s10, s12
	s_addc_u32 s15, s11, 0
	s_add_u32 s14, s14, 0x1400
	s_addc_u32 s15, s15, 0
	s_add_u32 s16, s10, 0x3400
	s_addc_u32 s17, s11, 0
	v_mov_b32_e32 v4, 1
	global_atomic_add v5, v161, v4, s[14:15] sc0
	s_waitcnt lgkmcnt(0)
	v_readfirstlane_b32 s18, v2
	v_readfirstlane_b32 s19, v3
	v_cvt_f32_u32_e32 v7, v2
	v_rcp_f32_e32 v7, v7
	s_waitcnt vmcnt(0)
	v_readfirstlane_b32 s13, v5
	v_cvt_f32_u32_e32 v6, v5
	v_mul_f32_e32 v6, v6, v7
	v_cvt_u32_f32_e32 v6, v6
	s_nop 0
	v_readfirstlane_b32 s2, v6
	s_mul_i32 s3, s2, s18
	s_cmp_gt_u32 s3, s13
	s_cbranch_scc0 .Lxb1_a
	s_sub_i32 s2, s2, 1
	s_sub_i32 s3, s3, s18

; __device__ __forceinline__ unsigned xb_ld(unsigned* p)              { return __hip_atomic_load(p, __ATOMIC_RELAXED, __HIP_MEMORY_SCOPE_AGENT); }
; __device__ __forceinline__ unsigned xb_add(unsigned* p, unsigned v) { return __hip_atomic_fetch_add(p, v, __ATOMIC_RELAXED, __HIP_MEMORY_SCOPE_AGENT); }
; #define XB_SPIN(cond, bar) do { unsigned _sp = 0; while (cond) { __builtin_amdgcn_s_sleep(1); \
;     if ((++_sp & 255u) == 0u) { if (xb_ld(&(bar)[XB_TMO])) break; if (_sp > XB_SPIN_CAP) { atomicAdd(&(bar)[XB_TMO], 1u); break; } } } } while (0)
; __device__ __forceinline__ void xcd_barrier(const XcdBarrier& b) {
;     asm volatile("s_waitcnt vmcnt(0)" ::: "memory");
;     __syncthreads();
;     if (threadIdx.x == 0) {
;         unsigned* bar = b.bar; unsigned bx = b.x; asm volatile("" : "+s"(bx));
;         __builtin_amdgcn_s_waitcnt(0);
;         unsigned nloc = b.st[0], nx = b.st[1];
;         if (nloc == 0u) { xcd_barrier_complete(bar, bx, nloc, nx); b.st[0] = nloc; b.st[1] = nx; }
;         const unsigned old = xb_add(&bar[XB_XSUB(bx)], 1u);
;         const unsigned gen = old / nloc;
;         if (old + 1u == (gen + 1u) * nloc) {
;             __builtin_amdgcn_fence(__ATOMIC_RELEASE, "agent");
;             asm volatile("s_waitcnt vmcnt(0)" ::: "memory");
;             const unsigned og = xb_add(&bar[XB_TOP], 1u);
;             const unsigned tg = og / nx;
;             if (og + 1u == (tg + 1u) * nx) xb_add(&bar[XB_TOPGEN], 1u);
;             else XB_SPIN(xb_ld(&bar[XB_TOPGEN]) == tg, bar);
;             __builtin_amdgcn_fence(__ATOMIC_ACQUIRE, "agent");
;             xb_add(&bar[XB_XGEN(bx)], 1u);
;             asm volatile("s_waitcnt vmcnt(0)" ::: "memory");
;         } else {
;             XB_SPIN(xb_ld(&bar[XB_XGEN(bx)]) == gen, bar);
;             __builtin_amdgcn_fence(__ATOMIC_ACQUIRE, "agent");
;             asm volatile("s_waitcnt vmcnt(0)" ::: "memory");
;         }
.LBB0_482:
	s_or_b64 exec, exec, s[0:1]
	s_waitcnt vmcnt(0)
	s_barrier
	s_mov_b64 s[0:1], exec
	v_readlane_b32 s2, v252, 3
	v_readlane_b32 s3, v252, 4
	s_and_b64 s[2:3], s[0:1], s[2:3]
	s_mov_b64 exec, s[2:3]
	s_cbranch_execz .LBB0_534
	s_waitcnt vmcnt(0) lgkmcnt(0)
	v_mov_b32_e32 v0, 0x26800
	ds_read_b32 v2, v0
	ds_read_b32 v3, v0 offset:4
	v_readlane_b32 s10, v252, 0
	v_readlane_b32 s11, v252, 1
	v_readlane_b32 s12, v252, 2
	s_lshl_b32 s12, s12, 8
	s_add_u32 s14, s10, s12
	s_addc_u32 s15, s11, 0
	s_add_u32 s14, s14, 0x1400
	s_addc_u32 s15, s15, 0
	s_add_u32 s16, s10, 0x3400
	s_addc_u32 s17, s11, 0
	v_mov_b32_e32 v4, 1
	global_atomic_add v5, v161, v4, s[14:15] sc0
	s_waitcnt lgkmcnt(0)
	v_readfirstlane_b32 s18, v2
	v_readfirstlane_b32 s19, v3
	v_cvt_f32_u32_e32 v7, v2
	v_rcp_f32_e32 v7, v7
	s_waitcnt vmcnt(0)
	v_readfirstlane_b32 s13, v5
	v_cvt_f32_u32_e32 v6, v5
	v_mul_f32_e32 v6, v6, v7
	v_cvt_u32_f32_e32 v6, v6
	s_nop 0
	v_readfirstlane_b32 s2, v6
	s_mul_i32 s3, s2, s18
	s_cmp_gt_u32 s3, s13
	s_cbranch_scc0 .Lxb2_a
	s_sub_i32 s2, s2, 1
	s_sub_i32 s3, s3, s18

; __device__ __forceinline__ unsigned xb_ld(unsigned* p)              { return __hip_atomic_load(p, __ATOMIC_RELAXED, __HIP_MEMORY_SCOPE_AGENT); }
; __device__ __forceinline__ unsigned xb_add(unsigned* p, unsigned v) { return __hip_atomic_fetch_add(p, v, __ATOMIC_RELAXED, __HIP_MEMORY_SCOPE_AGENT); }
; #define XB_SPIN(cond, bar) do { unsigned _sp = 0; while (cond) { __builtin_amdgcn_s_sleep(1); \
;     if ((++_sp & 255u) == 0u) { if (xb_ld(&(bar)[XB_TMO])) break; if (_sp > XB_SPIN_CAP) { atomicAdd(&(bar)[XB_TMO], 1u); break; } } } } while (0)
; __device__ __forceinline__ void xcd_barrier(const XcdBarrier& b) {
;     asm volatile("s_waitcnt vmcnt(0)" ::: "memory");
;     __syncthreads();
;     if (threadIdx.x == 0) {
;         unsigned* bar = b.bar; unsigned bx = b.x; asm volatile("" : "+s"(bx));
;         __builtin_amdgcn_s_waitcnt(0);
;         unsigned nloc = b.st[0], nx = b.st[1];
;         if (nloc == 0u) { xcd_barrier_complete(bar, bx, nloc, nx); b.st[0] = nloc; b.st[1] = nx; }
;         const unsigned old = xb_add(&bar[XB_XSUB(bx)], 1u);
;         const unsigned gen = old / nloc;
;         if (old + 1u == (gen + 1u) * nloc) {
;             __builtin_amdgcn_fence(__ATOMIC_RELEASE, "agent");
;             asm volatile("s_waitcnt vmcnt(0)" ::: "memory");
;             const unsigned og = xb_add(&bar[XB_TOP], 1u);
;             const unsigned tg = og / nx;
;             if (og + 1u == (tg + 1u) * nx) xb_add(&bar[XB_TOPGEN], 1u);
;             else XB_SPIN(xb_ld(&bar[XB_TOPGEN]) == tg, bar);
;             __builtin_amdgcn_fence(__ATOMIC_ACQUIRE, "agent");
;             xb_add(&bar[XB_XGEN(bx)], 1u);
;             asm volatile("s_waitcnt vmcnt(0)" ::: "memory");
;         } else {
;             XB_SPIN(xb_ld(&bar[XB_XGEN(bx)]) == gen, bar);
;             __builtin_amdgcn_fence(__ATOMIC_ACQUIRE, "agent");
;             asm volatile("s_waitcnt vmcnt(0)" ::: "memory");
;         }
.LBB0_880:
	s_or_b64 exec, exec, s[0:1]
	s_waitcnt vmcnt(0)
	s_barrier
	s_mov_b64 s[0:1], exec
	v_readlane_b32 s2, v252, 3
	v_readlane_b32 s3, v252, 4
	s_and_b64 s[2:3], s[0:1], s[2:3]
	s_mov_b32 s26, 0xbfb8aa3b
	s_mov_b32 s27, 0x800000
	s_mov_b32 s28, 0x3f317217
	s_mov_b32 s29, 0x7f800000
	v_readlane_b32 s20, v254, 55
	v_readlane_b32 s21, v254, 56
	s_mov_b64 exec, s[2:3]
	s_cbranch_execz .LBB0_932
	s_waitcnt vmcnt(0) lgkmcnt(0)
	v_mov_b32_e32 v0, 0x26800
	ds_read_b32 v2, v0
	ds_read_b32 v3, v0 offset:4
	v_readlane_b32 s10, v252, 0
	v_readlane_b32 s11, v252, 1
	v_readlane_b32 s12, v252, 2
	s_lshl_b32 s12, s12, 8
	s_add_u32 s14, s10, s12
	s_addc_u32 s15, s11, 0
	s_add_u32 s14, s14, 0x1400
	s_addc_u32 s15, s15, 0
	s_add_u32 s16, s10, 0x3400
	s_addc_u32 s17, s11, 0
	v_mov_b32_e32 v4, 1
	global_atomic_add v5, v161, v4, s[14:15] sc0
	s_waitcnt lgkmcnt(0)
	v_readfirstlane_b32 s18, v2
	v_readfirstlane_b32 s19, v3
	v_cvt_f32_u32_e32 v7, v2
	v_rcp_f32_e32 v7, v7
	s_waitcnt vmcnt(0)
	v_readfirstlane_b32 s13, v5
	v_cvt_f32_u32_e32 v6, v5
	v_mul_f32_e32 v6, v6, v7
	v_cvt_u32_f32_e32 v6, v6
	s_nop 0
	v_readfirstlane_b32 s2, v6
	s_mul_i32 s3, s2, s18
	s_cmp_gt_u32 s3, s13
	s_cbranch_scc0 .Lxb3_a
	s_sub_i32 s2, s2, 1
	s_sub_i32 s3, s3, s18

; __device__ __forceinline__ unsigned xb_ld(unsigned* p)              { return __hip_atomic_load(p, __ATOMIC_RELAXED, __HIP_MEMORY_SCOPE_AGENT); }
; __device__ __forceinline__ unsigned xb_add(unsigned* p, unsigned v) { return __hip_atomic_fetch_add(p, v, __ATOMIC_RELAXED, __HIP_MEMORY_SCOPE_AGENT); }
; #define XB_SPIN(cond, bar) do { unsigned _sp = 0; while (cond) { __builtin_amdgcn_s_sleep(1); \
;     if ((++_sp & 255u) == 0u) { if (xb_ld(&(bar)[XB_TMO])) break; if (_sp > XB_SPIN_CAP) { atomicAdd(&(bar)[XB_TMO], 1u); break; } } } } while (0)
; __device__ __forceinline__ void xcd_barrier(const XcdBarrier& b) {
;     asm volatile("s_waitcnt vmcnt(0)" ::: "memory");
;     __syncthreads();
;     if (threadIdx.x == 0) {
;         unsigned* bar = b.bar; unsigned bx = b.x; asm volatile("" : "+s"(bx));
;         __builtin_amdgcn_s_waitcnt(0);
;         unsigned nloc = b.st[0], nx = b.st[1];
;         if (nloc == 0u) { xcd_barrier_complete(bar, bx, nloc, nx); b.st[0] = nloc; b.st[1] = nx; }
;         const unsigned old = xb_add(&bar[XB_XSUB(bx)], 1u);
;         const unsigned gen = old / nloc;
;         if (old + 1u == (gen + 1u) * nloc) {
;             __builtin_amdgcn_fence(__ATOMIC_RELEASE, "agent");
;             asm volatile("s_waitcnt vmcnt(0)" ::: "memory");
;             const unsigned og = xb_add(&bar[XB_TOP], 1u);
;             const unsigned tg = og / nx;
;             if (og + 1u == (tg + 1u) * nx) xb_add(&bar[XB_TOPGEN], 1u);
;             else XB_SPIN(xb_ld(&bar[XB_TOPGEN]) == tg, bar);
;             __builtin_amdgcn_fence(__ATOMIC_ACQUIRE, "agent");
;             xb_add(&bar[XB_XGEN(bx)], 1u);
;             asm volatile("s_waitcnt vmcnt(0)" ::: "memory");
;         } else {
;             XB_SPIN(xb_ld(&bar[XB_XGEN(bx)]) == gen, bar);
;             __builtin_amdgcn_fence(__ATOMIC_ACQUIRE, "agent");
;             asm volatile("s_waitcnt vmcnt(0)" ::: "memory");
;         }
.LBB0_1070:
	s_waitcnt vmcnt(0)
	s_waitcnt lgkmcnt(0)
	s_barrier
	s_mov_b64 s[0:1], exec
	v_readlane_b32 s2, v252, 3
	v_readlane_b32 s3, v252, 4
	s_and_b64 s[2:3], s[0:1], s[2:3]
	s_mov_b64 s[30:31], 0x2000
	s_mov_b64 exec, s[2:3]
	s_cbranch_execz .LBB0_1122
	s_waitcnt vmcnt(0) lgkmcnt(0)
	v_mov_b32_e32 v0, 0x26800
	ds_read_b32 v2, v0
	ds_read_b32 v3, v0 offset:4
	v_readlane_b32 s10, v252, 0
	v_readlane_b32 s11, v252, 1
	v_readlane_b32 s12, v252, 2
	s_lshl_b32 s12, s12, 8
	s_add_u32 s14, s10, s12
	s_addc_u32 s15, s11, 0
	s_add_u32 s14, s14, 0x1400
	s_addc_u32 s15, s15, 0
	s_add_u32 s16, s10, 0x3400
	s_addc_u32 s17, s11, 0
	v_mov_b32_e32 v4, 1
	global_atomic_add v5, v161, v4, s[14:15] sc0
	s_waitcnt lgkmcnt(0)
	v_readfirstlane_b32 s18, v2
	v_readfirstlane_b32 s19, v3
	v_cvt_f32_u32_e32 v7, v2
	v_rcp_f32_e32 v7, v7
	s_waitcnt vmcnt(0)
	v_readfirstlane_b32 s13, v5
	v_cvt_f32_u32_e32 v6, v5
	v_mul_f32_e32 v6, v6, v7
	v_cvt_u32_f32_e32 v6, v6
	s_nop 0
	v_readfirstlane_b32 s2, v6
	s_mul_i32 s3, s2, s18
	s_cmp_gt_u32 s3, s13
	s_cbranch_scc0 .Lxb4_a
	s_sub_i32 s2, s2, 1
	s_sub_i32 s3, s3, s18

; __device__ __forceinline__ unsigned xb_ld(unsigned* p)              { return __hip_atomic_load(p, __ATOMIC_RELAXED, __HIP_MEMORY_SCOPE_AGENT); }
; __device__ __forceinline__ unsigned xb_add(unsigned* p, unsigned v) { return __hip_atomic_fetch_add(p, v, __ATOMIC_RELAXED, __HIP_MEMORY_SCOPE_AGENT); }
; #define XB_SPIN(cond, bar) do { unsigned _sp = 0; while (cond) { __builtin_amdgcn_s_sleep(1); \
;     if ((++_sp & 255u) == 0u) { if (xb_ld(&(bar)[XB_TMO])) break; if (_sp > XB_SPIN_CAP) { atomicAdd(&(bar)[XB_TMO], 1u); break; } } } } while (0)
; __device__ __forceinline__ void xcd_barrier(const XcdBarrier& b) {
;     asm volatile("s_waitcnt vmcnt(0)" ::: "memory");
;     __syncthreads();
;     if (threadIdx.x == 0) {
;         unsigned* bar = b.bar; unsigned bx = b.x; asm volatile("" : "+s"(bx));
;         __builtin_amdgcn_s_waitcnt(0);
;         unsigned nloc = b.st[0], nx = b.st[1];
;         if (nloc == 0u) { xcd_barrier_complete(bar, bx, nloc, nx); b.st[0] = nloc; b.st[1] = nx; }
;         const unsigned old = xb_add(&bar[XB_XSUB(bx)], 1u);
;         const unsigned gen = old / nloc;
;         if (old + 1u == (gen + 1u) * nloc) {
;             __builtin_amdgcn_fence(__ATOMIC_RELEASE, "agent");
;             asm volatile("s_waitcnt vmcnt(0)" ::: "memory");
;             const unsigned og = xb_add(&bar[XB_TOP], 1u);
;             const unsigned tg = og / nx;
;             if (og + 1u == (tg + 1u) * nx) xb_add(&bar[XB_TOPGEN], 1u);
;             else XB_SPIN(xb_ld(&bar[XB_TOPGEN]) == tg, bar);
;             __builtin_amdgcn_fence(__ATOMIC_ACQUIRE, "agent");
;             xb_add(&bar[XB_XGEN(bx)], 1u);
;             asm volatile("s_waitcnt vmcnt(0)" ::: "memory");
;         } else {
;             XB_SPIN(xb_ld(&bar[XB_XGEN(bx)]) == gen, bar);
;             __builtin_amdgcn_fence(__ATOMIC_ACQUIRE, "agent");
;             asm volatile("s_waitcnt vmcnt(0)" ::: "memory");
;         }
.LBB0_1352:
	s_waitcnt vmcnt(0) lgkmcnt(0)
	v_mov_b32_e32 v0, 0x26800
	ds_read_b32 v2, v0
	ds_read_b32 v3, v0 offset:4
	v_readlane_b32 s10, v252, 0
	v_readlane_b32 s11, v252, 1
	v_readlane_b32 s12, v252, 2
	s_lshl_b32 s12, s12, 8
	s_add_u32 s14, s10, s12
	s_addc_u32 s15, s11, 0
	s_add_u32 s14, s14, 0x1400
	s_addc_u32 s15, s15, 0
	s_add_u32 s16, s10, 0x3400
	s_addc_u32 s17, s11, 0
	v_mov_b32_e32 v4, 1
	global_atomic_add v5, v161, v4, s[14:15] sc0
	s_waitcnt lgkmcnt(0)
	v_readfirstlane_b32 s18, v2
	v_readfirstlane_b32 s19, v3
	v_cvt_f32_u32_e32 v7, v2
	v_rcp_f32_e32 v7, v7
	s_waitcnt vmcnt(0)
	v_readfirstlane_b32 s13, v5
	v_cvt_f32_u32_e32 v6, v5
	v_mul_f32_e32 v6, v6, v7
	v_cvt_u32_f32_e32 v6, v6
	s_nop 0
	v_readfirstlane_b32 s2, v6
	s_mul_i32 s3, s2, s18
	s_cmp_gt_u32 s3, s13
	s_cbranch_scc0 .Lxb6_a
	s_sub_i32 s2, s2, 1
	s_sub_i32 s3, s3, s18

; __device__ __forceinline__ unsigned xb_ld(unsigned* p)              { return __hip_atomic_load(p, __ATOMIC_RELAXED, __HIP_MEMORY_SCOPE_AGENT); }
; __device__ __forceinline__ unsigned xb_add(unsigned* p, unsigned v) { return __hip_atomic_fetch_add(p, v, __ATOMIC_RELAXED, __HIP_MEMORY_SCOPE_AGENT); }
; #define XB_SPIN(cond, bar) do { unsigned _sp = 0; while (cond) { __builtin_amdgcn_s_sleep(1); \
;     if ((++_sp & 255u) == 0u) { if (xb_ld(&(bar)[XB_TMO])) break; if (_sp > XB_SPIN_CAP) { atomicAdd(&(bar)[XB_TMO], 1u); break; } } } } while (0)
; __device__ __forceinline__ void xcd_barrier(const XcdBarrier& b) {
;     ...
;             __builtin_amdgcn_fence(__ATOMIC_ACQUIRE, "agent");
;             xb_add(&bar[XB_XGEN(bx)], 1u);
;             asm volatile("s_waitcnt vmcnt(0)" ::: "memory");
;         } else {
;             XB_SPIN(xb_ld(&bar[XB_XGEN(bx)]) == gen, bar);
;             __builtin_amdgcn_fence(__ATOMIC_ACQUIRE, "agent");
;             asm volatile("s_waitcnt vmcnt(0)" ::: "memory");
;         }
;     }
;     __syncthreads();
.Lxb6_go:
	buffer_inv sc1
	s_waitcnt vmcnt(0)
	s_mov_b64 s[4:5], 0
	s_getpc_b64 s[98:99]
